# grid barrier polls: leader back-off 28 -> 6, follower 8 -> 3 (shorter detection latency at each of the 19 barriers)
# speedup vs baseline: 1.0008x; 1.0008x over previous
; DEV void grid_barrier(unsigned* cnt, const unsigned target, const int tid) {
;     asm volatile("s_waitcnt vmcnt(0)" ::: "memory");
;     __syncthreads();
;     if (tid == 0) {
;         __builtin_amdgcn_fence(__ATOMIC_RELEASE, "agent");
;         __hip_atomic_fetch_add(cnt, 1u, __ATOMIC_RELAXED, __HIP_MEMORY_SCOPE_AGENT);
;         while (__hip_atomic_load(cnt, __ATOMIC_RELAXED, __HIP_MEMORY_SCOPE_AGENT) < target) __builtin_amdgcn_s_sleep(28);
;         __builtin_amdgcn_fence(__ATOMIC_ACQUIRE, "agent");
;         asm volatile("s_waitcnt vmcnt(0)" ::: "memory");
;     }
;     __syncthreads();
; }
.Lgb0_ptop:
	global_load_dword v4, v5, s[4:5] sc1
	s_waitcnt vmcnt(0)
	v_cmp_gt_u32_e32 vcc, s9, v4
	s_cbranch_vccz .Lgb0_tdone
	s_sleep 6
	s_branch .Lgb0_ptop

; DEV void grid_barrier(unsigned* cnt, const unsigned target, const int tid) {
;     asm volatile("s_waitcnt vmcnt(0)" ::: "memory");
;     __syncthreads();
;     if (tid == 0) {
;         __builtin_amdgcn_fence(__ATOMIC_RELEASE, "agent");
;         __hip_atomic_fetch_add(cnt, 1u, __ATOMIC_RELAXED, __HIP_MEMORY_SCOPE_AGENT);
;         while (__hip_atomic_load(cnt, __ATOMIC_RELAXED, __HIP_MEMORY_SCOPE_AGENT) < target) __builtin_amdgcn_s_sleep(28);
;         __builtin_amdgcn_fence(__ATOMIC_ACQUIRE, "agent");
;         asm volatile("s_waitcnt vmcnt(0)" ::: "memory");
;     }
;     __syncthreads();
; }
.Lgb0_follow:
.Lgb0_poll:
	global_load_dword v4, v2, s[4:5] offset:32 sc1
	s_waitcnt vmcnt(0)
	v_cmp_gt_u32_e32 vcc, s7, v4
	s_cbranch_vccz .Lgb0_done
	s_sleep 3
	s_branch .Lgb0_poll

; DEV void grid_barrier(unsigned* cnt, const unsigned target, const int tid) {
;     asm volatile("s_waitcnt vmcnt(0)" ::: "memory");
;     __syncthreads();
;     if (tid == 0) {
;         __builtin_amdgcn_fence(__ATOMIC_RELEASE, "agent");
;         __hip_atomic_fetch_add(cnt, 1u, __ATOMIC_RELAXED, __HIP_MEMORY_SCOPE_AGENT);
;         while (__hip_atomic_load(cnt, __ATOMIC_RELAXED, __HIP_MEMORY_SCOPE_AGENT) < target) __builtin_amdgcn_s_sleep(28);
;         __builtin_amdgcn_fence(__ATOMIC_ACQUIRE, "agent");
;         asm volatile("s_waitcnt vmcnt(0)" ::: "memory");
;     }
;     __syncthreads();
; }
.Lgb1_ptop:
	global_load_dword v4, v5, s[4:5] sc1
	s_waitcnt vmcnt(0)
	v_cmp_gt_u32_e32 vcc, s13, v4
	s_cbranch_vccz .Lgb1_tdone
	s_sleep 6
	s_branch .Lgb1_ptop

; DEV void grid_barrier(unsigned* cnt, const unsigned target, const int tid) {
;     asm volatile("s_waitcnt vmcnt(0)" ::: "memory");
;     __syncthreads();
;     if (tid == 0) {
;         __builtin_amdgcn_fence(__ATOMIC_RELEASE, "agent");
;         __hip_atomic_fetch_add(cnt, 1u, __ATOMIC_RELAXED, __HIP_MEMORY_SCOPE_AGENT);
;         while (__hip_atomic_load(cnt, __ATOMIC_RELAXED, __HIP_MEMORY_SCOPE_AGENT) < target) __builtin_amdgcn_s_sleep(28);
;         __builtin_amdgcn_fence(__ATOMIC_ACQUIRE, "agent");
;         asm volatile("s_waitcnt vmcnt(0)" ::: "memory");
;     }
;     __syncthreads();
; }
.Lgb1_follow:
.Lgb1_poll:
	global_load_dword v4, v2, s[4:5] offset:64 sc1
	s_waitcnt vmcnt(0)
	v_cmp_gt_u32_e32 vcc, s7, v4
	s_cbranch_vccz .Lgb1_done
	s_sleep 3
	s_branch .Lgb1_poll

; DEV void grid_barrier(unsigned* cnt, const unsigned target, const int tid) {
;     asm volatile("s_waitcnt vmcnt(0)" ::: "memory");
;     __syncthreads();
;     if (tid == 0) {
;         __builtin_amdgcn_fence(__ATOMIC_RELEASE, "agent");
;         __hip_atomic_fetch_add(cnt, 1u, __ATOMIC_RELAXED, __HIP_MEMORY_SCOPE_AGENT);
;         while (__hip_atomic_load(cnt, __ATOMIC_RELAXED, __HIP_MEMORY_SCOPE_AGENT) < target) __builtin_amdgcn_s_sleep(28);
;         __builtin_amdgcn_fence(__ATOMIC_ACQUIRE, "agent");
;         asm volatile("s_waitcnt vmcnt(0)" ::: "memory");
;     }
;     __syncthreads();
; }
.Lgb2_ptop:
	global_load_dword v4, v5, s[2:3] sc1
	s_waitcnt vmcnt(0)
	v_cmp_gt_u32_e32 vcc, s7, v4
	s_cbranch_vccz .Lgb2_tdone
	s_sleep 6
	s_branch .Lgb2_ptop

; DEV void grid_barrier(unsigned* cnt, const unsigned target, const int tid) {
;     asm volatile("s_waitcnt vmcnt(0)" ::: "memory");
;     __syncthreads();
;     if (tid == 0) {
;         __builtin_amdgcn_fence(__ATOMIC_RELEASE, "agent");
;         __hip_atomic_fetch_add(cnt, 1u, __ATOMIC_RELAXED, __HIP_MEMORY_SCOPE_AGENT);
;         while (__hip_atomic_load(cnt, __ATOMIC_RELAXED, __HIP_MEMORY_SCOPE_AGENT) < target) __builtin_amdgcn_s_sleep(28);
;         __builtin_amdgcn_fence(__ATOMIC_ACQUIRE, "agent");
;         asm volatile("s_waitcnt vmcnt(0)" ::: "memory");
;     }
;     __syncthreads();
; }
.Lgb2_follow:
.Lgb2_poll:
	global_load_dword v4, v2, s[2:3] offset:64 sc1
	s_waitcnt vmcnt(0)
	v_cmp_gt_u32_e32 vcc, s5, v4
	s_cbranch_vccz .Lgb2_done
	s_sleep 3
	s_branch .Lgb2_poll
